# P0: workgroups without a modulation item hold their first loads back (s_sleep 100) so the modulation items' cold loads see less contention
# speedup vs baseline: 1.0012x; 1.0012x over previous
.LBB0_14:
	s_load_dwordx2 s[38:39], s[6:7], 0x0
	s_load_dwordx2 s[40:41], s[6:7], 0x90
	s_waitcnt lgkmcnt(0)
	s_add_u32 s24, s36, 0x80000
	s_addc_u32 s25, s37, 0
	s_cmpk_gt_i32 s71, 0xbf
	s_cbranch_scc0 .Lp0hold_skip
	s_sleep 100
.Lp0hold_skip:
	v_mov_b32_e32 v66, 0
	s_andn2_b64 vcc, exec, s[4:5]
	v_mov_b32_e32 v67, 0
	s_cbranch_vccnz .LBB0_18
	s_waitcnt vmcnt(7)
	v_mul_f32_e32 v42, 0xbfb8aa3b, v41
	v_exp_f32_e32 v42, v42
	s_lshl_b32 s0, s71, 4
	s_andn2_b32 s0, s0, 63
	s_and_b32 s1, s71, 3
	v_add_f32_e32 v42, 1.0, v42
	v_rcp_f32_e32 v42, v42
	s_mov_b32 s5, 0
	s_cmp_lg_u32 s1, 0
	v_mul_f32_e32 v41, v41, v42
	s_nop 1
	v_mfma_f32_16x16x4_f32 v[50:53], v41, v31, 0
	s_waitcnt vmcnt(6)
	v_mul_f32_e32 v31, 0xbfb8aa3b, v40
	v_exp_f32_e32 v54, v31
	v_mfma_f32_16x16x4_f32 v[42:45], v41, v33, 0
	v_mfma_f32_16x16x4_f32 v[46:49], v41, v32, 0
	v_mfma_f32_16x16x4_f32 v[30:33], v41, v30, 0
	v_add_f32_e32 v41, 1.0, v54
	v_rcp_f32_e32 v41, v41
	s_nop 0
	v_mul_f32_e32 v54, v40, v41
	s_nop 1
	v_mfma_f32_16x16x4_f32 v[40:43], v54, v29, v[42:45]
	v_mfma_f32_16x16x4_f32 v[44:47], v54, v27, v[46:49]
	v_mfma_f32_16x16x4_f32 v[48:51], v54, v25, v[50:53]
	s_waitcnt vmcnt(5)
	v_mul_f32_e32 v25, 0xbfb8aa3b, v39
	v_exp_f32_e32 v25, v25
	v_mfma_f32_16x16x4_f32 v[30:33], v54, v23, v[30:33]
	v_add_f32_e32 v23, 1.0, v25
	v_rcp_f32_e32 v23, v23
	s_nop 0
	v_mul_f32_e32 v23, v39, v23
	s_nop 1
	v_mfma_f32_16x16x4_f32 v[40:43], v23, v28, v[40:43]
	v_mfma_f32_16x16x4_f32 v[26:29], v23, v26, v[44:47]
	v_mfma_f32_16x16x4_f32 v[44:47], v23, v24, v[48:51]
	s_waitcnt vmcnt(4)
	v_mul_f32_e32 v24, 0xbfb8aa3b, v38
	v_exp_f32_e32 v39, v24
	v_mfma_f32_16x16x4_f32 v[22:25], v23, v22, v[30:33]
	v_add_f32_e32 v30, 1.0, v39
	v_rcp_f32_e32 v30, v30
	s_nop 0
	v_mul_f32_e32 v48, v38, v30
	s_nop 1
	v_mfma_f32_16x16x4_f32 v[30:33], v48, v21, v[40:43]
	v_mfma_f32_16x16x4_f32 v[38:41], v48, v17, v[44:47]
	s_waitcnt vmcnt(3)
	v_mul_f32_e32 v17, 0xbfb8aa3b, v37
	v_exp_f32_e32 v17, v17
	v_mfma_f32_16x16x4_f32 v[22:25], v48, v15, v[22:25]
	v_add_f32_e32 v15, 1.0, v17
	v_rcp_f32_e32 v15, v15
	s_nop 0
	v_mul_f32_e32 v15, v37, v15
	v_mfma_f32_16x16x4_f32 v[26:29], v48, v19, v[26:29]
	s_nop 0
	v_mfma_f32_16x16x4_f32 v[30:33], v15, v20, v[30:33]
	v_mfma_f32_16x16x4_f32 v[18:21], v15, v18, v[26:29]
	v_mfma_f32_16x16x4_f32 v[26:29], v15, v16, v[38:41]
	s_waitcnt vmcnt(2)
	v_mul_f32_e32 v16, 0xbfb8aa3b, v36
	v_exp_f32_e32 v37, v16
	v_mfma_f32_16x16x4_f32 v[14:17], v15, v14, v[22:25]
	v_add_f32_e32 v22, 1.0, v37
	v_rcp_f32_e32 v22, v22
	s_nop 0
	v_mul_f32_e32 v36, v36, v22
	s_nop 1
	v_mfma_f32_16x16x4_f32 v[26:29], v36, v9, v[26:29]
	s_waitcnt vmcnt(1)
	v_mul_f32_e32 v9, 0xbfb8aa3b, v35
	v_exp_f32_e32 v9, v9
	v_mfma_f32_16x16x4_f32 v[14:17], v36, v7, v[14:17]
	v_add_f32_e32 v7, 1.0, v9
	v_rcp_f32_e32 v7, v7
	s_nop 0
	v_mul_f32_e32 v7, v35, v7
	v_mfma_f32_16x16x4_f32 v[22:25], v36, v13, v[30:33]
	v_mfma_f32_16x16x4_f32 v[18:21], v36, v11, v[18:21]
	v_mfma_f32_16x16x4_f32 v[22:25], v7, v12, v[22:25]
	v_mfma_f32_16x16x4_f32 v[10:13], v7, v10, v[18:21]
	v_mfma_f32_16x16x4_f32 v[18:21], v7, v8, v[26:29]
	s_waitcnt vmcnt(0)
	v_mul_f32_e32 v8, 0xbfb8aa3b, v34
	v_exp_f32_e32 v26, v8
	v_mfma_f32_16x16x4_f32 v[6:9], v7, v6, v[14:17]
	v_add_f32_e32 v14, 1.0, v26
	v_rcp_f32_e32 v14, v14
	s_nop 0
	v_mul_f32_e32 v26, v34, v14
	s_nop 1
	v_mfma_f32_16x16x4_f32 v[14:17], v26, v5, v[22:25]
	v_lshlrev_b32_e32 v5, 6, v0
	v_mfma_f32_16x16x4_f32 v[10:13], v26, v4, v[10:13]
	v_and_b32_e32 v4, 15, v0
	v_lshlrev_b32_e32 v4, 2, v4
	v_mfma_f32_16x16x4_f32 v[18:21], v26, v3, v[18:21]
	v_and_b32_e32 v3, 0xc00, v5
	v_lshl_or_b32 v3, s72, 12, v3
	v_add3_u32 v22, 0, v4, v3
	s_nop 3
	ds_write2_b32 v22, v14, v10 offset1:16
	ds_write2_b32 v22, v15, v11 offset0:64 offset1:80
	ds_write2_b32 v22, v16, v12 offset0:128 offset1:144
	ds_write2_b32 v22, v17, v13 offset0:192 offset1:208
	v_mfma_f32_16x16x4_f32 v[2:5], v26, v2, v[6:9]
	s_nop 9
	ds_write2_b32 v22, v18, v2 offset0:32 offset1:48
	ds_write2_b32 v22, v19, v3 offset0:96 offset1:112
	ds_write2_b32 v22, v20, v4 offset0:160 offset1:176
	ds_write2_b32 v22, v21, v5 offset0:224 offset1:240
	v_or_b32_e32 v2, s0, v252
	v_ashrrev_i32_e32 v3, 31, v2
	v_mov_b32_e32 v4, 0
	s_waitcnt lgkmcnt(0)
	s_barrier
	s_cbranch_scc1 .LBB0_17
	v_mov_b32_e32 v4, s12
	v_mov_b32_e32 v5, s13
	v_lshl_add_u64 v[4:5], v[2:3], 2, v[4:5]
	global_load_dword v4, v[4:5], off
